# as v50 + hand-written in-projection epilogue (32-bit saddr addressing, layout branch taken once per tile instead of per store)
# baseline (speedup 1.0000x reference)
; #define PG8_STAGE(bufoff, gbase, voff) do { _Pragma("unroll") for (int _i = 0; _i < 2; ++_i) \
;         __builtin_amdgcn_global_load_lds((const unsigned*)((const char*)(gbase) + (voff)[_i]), (LAS unsigned*)(lds + (bufoff) + ldsw + _i * 8192), 16, 0, 0); } while (0)
; #define PG8_LDA(dst, b, h) do { _Pragma("unroll") for (int m = 0; m < 4; ++m) _Pragma("unroll") for (int k = 0; k < 2; ++k) dst[m][k] = *(const LAS bf16x8*)(lds + PG8_SA(b, h) + aoff + m * 2048 + k * 1024); } while (0)
; #define PG8_LDB(dst, b, h) do { _Pragma("unroll") for (int n = 0; n < 2; ++n) _Pragma("unroll") for (int k = 0; k < 2; ++k) dst[n][k] = *(const LAS bf16x8*)(lds + PG8_SB(b, h) + boff + n * 2048 + k * 1024); } while (0)
; #define PG8_MMA(ai, bj, At, Bt) do { __builtin_amdgcn_s_setprio(1); _Pragma("unroll") for (int m = 0; m < 4; ++m) _Pragma("unroll") for (int n = 0; n < 2; ++n) _Pragma("unroll") for (int k = 0; k < 2; ++k) \
;         acc[ai][bj][m][n] = __builtin_amdgcn_mfma_f32_16x16x32_bf16(Bt[n][k], At[m][k], acc[ai][bj][m][n], 0, 0, 0); __builtin_amdgcn_s_setprio(0); } while (0)
; #define PG8_WAIT_V(n) asm volatile("s_waitcnt vmcnt(" #n ")" ::: "memory")
; #define PG8_WAIT_L(n) asm volatile("s_waitcnt lgkmcnt(" #n ")" ::: "memory")
; template <class Epi>
; __device__ __forceinline__ void gemm_phase(LAS unsigned char* lds, const Gemm g, const StaticOrder& S, const Epi& E) {
;     ...
;         for (int t = 0; t < nt; t += 2) {
;             const bool last = (t == nt - 2);
;             const char* a1 = cA + (size_t)(t + 1) * kstepA;
;             const char* a2 = last ? nA : cA + (size_t)(t + 2) * kstepA; const char* b2 = last ? nB : cB + (size_t)(t + 2) * kstep;
;             const char* a3 = a2 + kstepA; const char* b3 = b2 + kstep;
;             PG8_LDB(B0, 0, 0); PG8_SCHED; PG8_LDA(At, 0, 0); PG8_STAGE(PG8_SA(1, 1), a1 + hstepA, voffA);
;             PG8_WAIT_L(8); PG8_BAR; PG8_WAIT_L(0); PG8_MMA(0, 0, At, B0); PG8_BAR; PG8_SCHED;
;             PG8_LDB(B1, 0, 1); PG8_STAGE(PG8_SB(0, 0), b2, voffB);
;             PG8_BAR; PG8_WAIT_L(0); PG8_MMA(0, 1, At, B1); PG8_BAR;
;             PG8_LDA(At, 0, 1); PG8_STAGE(PG8_SA(0, 0), a2, voffA);
;             PG8_BAR; PG8_WAIT_L(0); PG8_MMA(1, 0, At, B0); PG8_BAR; PG8_SCHED;
;             PG8_STAGE(PG8_SB(0, 1), b2 + hstepB, voffB);
;             PG8_WAIT_V(6); PG8_BAR; PG8_MMA(1, 1, At, B1); PG8_BAR;
.LBB0_158:
	s_add_u32 s42, s38, 0x100
	s_addc_u32 s43, s39, 0
	s_add_i32 s60, 0, 0x10000
	ds_read_b128 v[146:149], v250
	ds_read_b128 v[162:165], v250 offset:1024
	ds_read_b128 v[166:169], v250 offset:2048
	ds_read_b128 v[170:173], v250 offset:3072
	s_cmp_eq_u32 s59, 28
	s_cselect_b32 s25, s23, s43
	s_cselect_b32 s24, s55, s42
	s_cselect_b32 s5, s21, s58
	s_cselect_b32 s4, s56, s57
	s_add_i32 m0, s46, 0xc000
	ds_read_b128 v[174:177], v154
	ds_read_b128 v[188:191], v154 offset:1024
	ds_read_b128 v[192:195], v154 offset:2048
	ds_read_b128 v[196:199], v154 offset:3072
	ds_read_b128 v[200:203], v154 offset:4096
	ds_read_b128 v[204:207], v154 offset:5120
	ds_read_b128 v[208:211], v154 offset:6144
	ds_read_b128 v[212:215], v154 offset:7168
	global_load_lds_dwordx4 v140, s[38:39]
	s_add_i32 m0, s46, 0xe000
	s_nop 0
	global_load_lds_dwordx4 v142, s[38:39]
	s_waitcnt lgkmcnt(8)
	s_barrier
	s_waitcnt lgkmcnt(0)
	v_mfma_f32_16x16x32_bf16 v[126:129], v[146:149], v[174:177], v[126:129]
	v_mfma_f32_16x16x32_bf16 v[122:125], v[166:169], v[174:177], v[122:125]
	v_mfma_f32_16x16x32_bf16 v[110:113], v[146:149], v[192:195], v[110:113]
	v_mfma_f32_16x16x32_bf16 v[106:109], v[166:169], v[192:195], v[106:109]
	v_mfma_f32_16x16x32_bf16 v[94:97], v[146:149], v[200:203], v[94:97]
	v_mfma_f32_16x16x32_bf16 v[90:93], v[166:169], v[200:203], v[90:93]
	v_mfma_f32_16x16x32_bf16 v[78:81], v[146:149], v[208:211], v[78:81]
	v_mfma_f32_16x16x32_bf16 v[74:77], v[166:169], v[208:211], v[74:77]
	v_mfma_f32_16x16x32_bf16 v[126:129], v[162:165], v[188:191], v[126:129]
	v_mfma_f32_16x16x32_bf16 v[122:125], v[170:173], v[188:191], v[122:125]
	v_mfma_f32_16x16x32_bf16 v[110:113], v[162:165], v[196:199], v[110:113]
	v_mfma_f32_16x16x32_bf16 v[106:109], v[170:173], v[196:199], v[106:109]
	v_mfma_f32_16x16x32_bf16 v[94:97], v[162:165], v[204:207], v[94:97]
	v_mfma_f32_16x16x32_bf16 v[90:93], v[170:173], v[204:207], v[90:93]
	v_mfma_f32_16x16x32_bf16 v[78:81], v[162:165], v[212:215], v[78:81]
	v_mfma_f32_16x16x32_bf16 v[74:77], v[170:173], v[212:215], v[74:77]
	s_barrier
	s_add_i32 s61, 0, 0x14000
	s_add_i32 s38, s60, s45
	s_add_u32 s100, s4, s6
	s_addc_u32 s101, s5, s7
	s_mov_b32 m0, s38
	ds_read_b128 v[216:219], v250 offset:16384
	ds_read_b128 v[220:223], v250 offset:17408
	ds_read_b128 v[224:227], v250 offset:18432
	ds_read_b128 v[228:231], v250 offset:19456
	global_load_lds_dwordx4 v134, s[4:5]
	s_add_i32 m0, s38, 0x2000
	s_nop 0
	global_load_lds_dwordx4 v130, s[4:5]
	s_barrier
	s_waitcnt lgkmcnt(0)
	v_mfma_f32_16x16x32_bf16 v[118:121], v[216:219], v[174:177], v[118:121]
	v_mfma_f32_16x16x32_bf16 v[114:117], v[224:227], v[174:177], v[114:117]
	v_mfma_f32_16x16x32_bf16 v[102:105], v[216:219], v[192:195], v[102:105]
	v_mfma_f32_16x16x32_bf16 v[98:101], v[224:227], v[192:195], v[98:101]
	v_mfma_f32_16x16x32_bf16 v[86:89], v[216:219], v[200:203], v[86:89]
	v_mfma_f32_16x16x32_bf16 v[82:85], v[224:227], v[200:203], v[82:85]
	v_mfma_f32_16x16x32_bf16 v[70:73], v[216:219], v[208:211], v[70:73]
	v_mfma_f32_16x16x32_bf16 v[66:69], v[224:227], v[208:211], v[66:69]
	v_mfma_f32_16x16x32_bf16 v[118:121], v[220:223], v[188:191], v[118:121]
	v_mfma_f32_16x16x32_bf16 v[114:117], v[228:231], v[188:191], v[114:117]
	v_mfma_f32_16x16x32_bf16 v[102:105], v[220:223], v[196:199], v[102:105]
	v_mfma_f32_16x16x32_bf16 v[98:101], v[228:231], v[196:199], v[98:101]
	v_mfma_f32_16x16x32_bf16 v[86:89], v[220:223], v[204:207], v[86:89]
	v_mfma_f32_16x16x32_bf16 v[82:85], v[228:231], v[204:207], v[82:85]
	v_mfma_f32_16x16x32_bf16 v[70:73], v[220:223], v[212:215], v[70:73]
	v_mfma_f32_16x16x32_bf16 v[66:69], v[228:231], v[212:215], v[66:69]
	s_mov_b32 m0, s46
	s_add_u32 vcc_lo, s24, s6
	s_addc_u32 vcc_hi, s25, s7
	s_barrier
	ds_read_b128 v[174:177], v154 offset:16384
	ds_read_b128 v[188:191], v154 offset:17408
	ds_read_b128 v[192:195], v154 offset:18432
	ds_read_b128 v[196:199], v154 offset:19456
	ds_read_b128 v[200:203], v154 offset:20480
	ds_read_b128 v[204:207], v154 offset:21504
	ds_read_b128 v[208:211], v154 offset:22528
	ds_read_b128 v[212:215], v154 offset:23552
	global_load_lds_dwordx4 v136, s[24:25]
	s_mov_b32 m0, s47
	s_nop 0
	global_load_lds_dwordx4 v132, s[24:25]
	s_barrier
	s_waitcnt lgkmcnt(0)
	v_mfma_f32_16x16x32_bf16 v[62:65], v[146:149], v[174:177], v[62:65]
	v_mfma_f32_16x16x32_bf16 v[58:61], v[166:169], v[174:177], v[58:61]
	v_mfma_f32_16x16x32_bf16 v[46:49], v[146:149], v[192:195], v[46:49]
	v_mfma_f32_16x16x32_bf16 v[42:45], v[166:169], v[192:195], v[42:45]
	v_mfma_f32_16x16x32_bf16 v[30:33], v[146:149], v[200:203], v[30:33]
	v_mfma_f32_16x16x32_bf16 v[26:29], v[166:169], v[200:203], v[26:29]
	v_mfma_f32_16x16x32_bf16 v[14:17], v[146:149], v[208:211], v[14:17]
	v_mfma_f32_16x16x32_bf16 v[10:13], v[166:169], v[208:211], v[10:13]
	v_mfma_f32_16x16x32_bf16 v[62:65], v[162:165], v[188:191], v[62:65]
	v_mfma_f32_16x16x32_bf16 v[58:61], v[170:173], v[188:191], v[58:61]
	v_mfma_f32_16x16x32_bf16 v[46:49], v[162:165], v[196:199], v[46:49]
	v_mfma_f32_16x16x32_bf16 v[42:45], v[170:173], v[196:199], v[42:45]
	v_mfma_f32_16x16x32_bf16 v[30:33], v[162:165], v[204:207], v[30:33]
	v_mfma_f32_16x16x32_bf16 v[26:29], v[170:173], v[204:207], v[26:29]
	v_mfma_f32_16x16x32_bf16 v[14:17], v[162:165], v[212:215], v[14:17]
	v_mfma_f32_16x16x32_bf16 v[10:13], v[170:173], v[212:215], v[10:13]
	s_barrier
	s_add_u32 s38, s4, 0x80000
	s_addc_u32 s39, s5, 0
	s_add_i32 s60, s61, s45
	s_mov_b32 m0, s60
	s_nop 0
	global_load_lds_dwordx4 v134, s[38:39]
	s_add_i32 m0, s60, 0x2000
	s_nop 0
	global_load_lds_dwordx4 v130, s[38:39]
	s_waitcnt vmcnt(6)
	s_barrier
; #define PG8_STAGE(bufoff, gbase, voff) do { _Pragma("unroll") for (int _i = 0; _i < 2; ++_i) \
;         __builtin_amdgcn_global_load_lds((const unsigned*)((const char*)(gbase) + (voff)[_i]), (LAS unsigned*)(lds + (bufoff) + ldsw + _i * 8192), 16, 0, 0); } while (0)
; #define PG8_LDA(dst, b, h) do { _Pragma("unroll") for (int m = 0; m < 4; ++m) _Pragma("unroll") for (int k = 0; k < 2; ++k) dst[m][k] = *(const LAS bf16x8*)(lds + PG8_SA(b, h) + aoff + m * 2048 + k * 1024); } while (0)
; #define PG8_LDB(dst, b, h) do { _Pragma("unroll") for (int n = 0; n < 2; ++n) _Pragma("unroll") for (int k = 0; k < 2; ++k) dst[n][k] = *(const LAS bf16x8*)(lds + PG8_SB(b, h) + boff + n * 2048 + k * 1024); } while (0)
; #define PG8_MMA(ai, bj, At, Bt) do { __builtin_amdgcn_s_setprio(1); _Pragma("unroll") for (int m = 0; m < 4; ++m) _Pragma("unroll") for (int n = 0; n < 2; ++n) _Pragma("unroll") for (int k = 0; k < 2; ++k) \
;         acc[ai][bj][m][n] = __builtin_amdgcn_mfma_f32_16x16x32_bf16(Bt[n][k], At[m][k], acc[ai][bj][m][n], 0, 0, 0); __builtin_amdgcn_s_setprio(0); } while (0)
; #define PG8_WAIT_V(n) asm volatile("s_waitcnt vmcnt(" #n ")" ::: "memory")
; #define PG8_WAIT_L(n) asm volatile("s_waitcnt lgkmcnt(" #n ")" ::: "memory")
; #define PG8_BAR __builtin_amdgcn_s_barrier()
; #define PG8_SCHED __builtin_amdgcn_sched_barrier(0)
; template <class Epi>
; __device__ __forceinline__ void gemm_phase(LAS unsigned char* lds, const Gemm g, const StaticOrder& S, const Epi& E) {
;     ...
;             PG8_WAIT_V(6); PG8_BAR; PG8_MMA(1, 1, At, B1); PG8_BAR;
;             PG8_LDB(B0, 1, 0); PG8_SCHED; PG8_LDA(At, 1, 0); PG8_STAGE(PG8_SA(0, 1), a2 + hstepA, voffA);
;             PG8_WAIT_L(8); PG8_BAR; PG8_WAIT_L(0); PG8_MMA(0, 0, At, B0); PG8_BAR; PG8_SCHED;
;             PG8_LDB(B1, 1, 1); PG8_STAGE(PG8_SB(1, 0), b3, voffB);
;             PG8_BAR; PG8_WAIT_L(0); PG8_MMA(0, 1, At, B1); PG8_BAR;
;             PG8_LDA(At, 1, 1); PG8_STAGE(PG8_SA(1, 0), a3, voffA);
;             PG8_BAR; PG8_WAIT_L(0); PG8_MMA(1, 0, At, B0); PG8_BAR; PG8_SCHED;
;             PG8_STAGE(PG8_SB(1, 1), b3 + hstepB, voffB);
;             PG8_WAIT_V(6); PG8_BAR; PG8_MMA(1, 1, At, B1); PG8_BAR;
	v_mfma_f32_16x16x32_bf16 v[54:57], v[216:219], v[174:177], v[54:57]
	v_mfma_f32_16x16x32_bf16 v[50:53], v[224:227], v[174:177], v[50:53]
	v_mfma_f32_16x16x32_bf16 v[38:41], v[216:219], v[192:195], v[38:41]
	v_mfma_f32_16x16x32_bf16 v[34:37], v[224:227], v[192:195], v[34:37]
	v_mfma_f32_16x16x32_bf16 v[22:25], v[216:219], v[200:203], v[22:25]
	v_mfma_f32_16x16x32_bf16 v[18:21], v[224:227], v[200:203], v[18:21]
	v_mfma_f32_16x16x32_bf16 v[6:9], v[216:219], v[208:211], v[6:9]
	v_mfma_f32_16x16x32_bf16 v[2:5], v[224:227], v[208:211], v[2:5]
	v_mfma_f32_16x16x32_bf16 v[54:57], v[220:223], v[188:191], v[54:57]
	v_mfma_f32_16x16x32_bf16 v[50:53], v[228:231], v[188:191], v[50:53]
	v_mfma_f32_16x16x32_bf16 v[38:41], v[220:223], v[196:199], v[38:41]
	v_mfma_f32_16x16x32_bf16 v[34:37], v[228:231], v[196:199], v[34:37]
	v_mfma_f32_16x16x32_bf16 v[22:25], v[220:223], v[204:207], v[22:25]
	v_mfma_f32_16x16x32_bf16 v[18:21], v[228:231], v[204:207], v[18:21]
	v_mfma_f32_16x16x32_bf16 v[6:9], v[220:223], v[212:215], v[6:9]
	v_mfma_f32_16x16x32_bf16 v[2:5], v[228:231], v[212:215], v[2:5]
	s_add_i32 s38, 0, 0x18000
	s_barrier
	ds_read_b128 v[146:149], v250 offset:32768
	ds_read_b128 v[162:165], v250 offset:33792
	ds_read_b128 v[166:169], v250 offset:34816
	ds_read_b128 v[170:173], v250 offset:35840
	s_add_u32 s24, s24, 0x80000
	s_addc_u32 s25, s25, 0
	s_mov_b32 m0, s48
	ds_read_b128 v[174:177], v154 offset:32768
	ds_read_b128 v[188:191], v154 offset:33792
	ds_read_b128 v[192:195], v154 offset:34816
	ds_read_b128 v[196:199], v154 offset:35840
	ds_read_b128 v[200:203], v154 offset:36864
	ds_read_b128 v[204:207], v154 offset:37888
	ds_read_b128 v[208:211], v154 offset:38912
	ds_read_b128 v[212:215], v154 offset:39936
	global_load_lds_dwordx4 v136, s[24:25]
	s_mov_b32 m0, s49
	s_nop 0
	global_load_lds_dwordx4 v132, s[24:25]
	s_waitcnt lgkmcnt(8)
	s_barrier
	s_waitcnt lgkmcnt(0)
	v_mfma_f32_16x16x32_bf16 v[126:129], v[146:149], v[174:177], v[126:129]
	v_mfma_f32_16x16x32_bf16 v[122:125], v[166:169], v[174:177], v[122:125]
	v_mfma_f32_16x16x32_bf16 v[110:113], v[146:149], v[192:195], v[110:113]
	v_mfma_f32_16x16x32_bf16 v[106:109], v[166:169], v[192:195], v[106:109]
	v_mfma_f32_16x16x32_bf16 v[94:97], v[146:149], v[200:203], v[94:97]
	v_mfma_f32_16x16x32_bf16 v[90:93], v[166:169], v[200:203], v[90:93]
	v_mfma_f32_16x16x32_bf16 v[78:81], v[146:149], v[208:211], v[78:81]
	v_mfma_f32_16x16x32_bf16 v[74:77], v[166:169], v[208:211], v[74:77]
	v_mfma_f32_16x16x32_bf16 v[126:129], v[162:165], v[188:191], v[126:129]
	v_mfma_f32_16x16x32_bf16 v[122:125], v[170:173], v[188:191], v[122:125]
	v_mfma_f32_16x16x32_bf16 v[110:113], v[162:165], v[196:199], v[110:113]
	v_mfma_f32_16x16x32_bf16 v[106:109], v[170:173], v[196:199], v[106:109]
	v_mfma_f32_16x16x32_bf16 v[94:97], v[162:165], v[204:207], v[94:97]
	v_mfma_f32_16x16x32_bf16 v[90:93], v[170:173], v[204:207], v[90:93]
	v_mfma_f32_16x16x32_bf16 v[78:81], v[162:165], v[212:215], v[78:81]
	v_mfma_f32_16x16x32_bf16 v[74:77], v[170:173], v[212:215], v[74:77]
	s_barrier
	s_add_i32 s24, 0, 0x1c000
	s_add_i32 s25, s38, s45
	s_mov_b32 m0, s25
	ds_read_b128 v[216:219], v250 offset:49152
	ds_read_b128 v[220:223], v250 offset:50176
	ds_read_b128 v[224:227], v250 offset:51200
	ds_read_b128 v[228:231], v250 offset:52224
	global_load_lds_dwordx4 v134, s[100:101]
	s_add_i32 m0, s25, 0x2000
	s_nop 0
	global_load_lds_dwordx4 v130, s[100:101]
	s_barrier
	s_waitcnt lgkmcnt(0)
	v_mfma_f32_16x16x32_bf16 v[118:121], v[216:219], v[174:177], v[118:121]
	v_mfma_f32_16x16x32_bf16 v[114:117], v[224:227], v[174:177], v[114:117]
	v_mfma_f32_16x16x32_bf16 v[102:105], v[216:219], v[192:195], v[102:105]
	v_mfma_f32_16x16x32_bf16 v[98:101], v[224:227], v[192:195], v[98:101]
	v_mfma_f32_16x16x32_bf16 v[86:89], v[216:219], v[200:203], v[86:89]
	v_mfma_f32_16x16x32_bf16 v[82:85], v[224:227], v[200:203], v[82:85]
	v_mfma_f32_16x16x32_bf16 v[70:73], v[216:219], v[208:211], v[70:73]
	v_mfma_f32_16x16x32_bf16 v[66:69], v[224:227], v[208:211], v[66:69]
	v_mfma_f32_16x16x32_bf16 v[118:121], v[220:223], v[188:191], v[118:121]
	v_mfma_f32_16x16x32_bf16 v[114:117], v[228:231], v[188:191], v[114:117]
	v_mfma_f32_16x16x32_bf16 v[102:105], v[220:223], v[196:199], v[102:105]
	v_mfma_f32_16x16x32_bf16 v[98:101], v[228:231], v[196:199], v[98:101]
	v_mfma_f32_16x16x32_bf16 v[86:89], v[220:223], v[204:207], v[86:89]
	v_mfma_f32_16x16x32_bf16 v[82:85], v[228:231], v[204:207], v[82:85]
	v_mfma_f32_16x16x32_bf16 v[70:73], v[220:223], v[212:215], v[70:73]
	v_mfma_f32_16x16x32_bf16 v[66:69], v[228:231], v[212:215], v[66:69]
	s_mov_b32 m0, s50
	s_barrier
	ds_read_b128 v[174:177], v154 offset:49152
	ds_read_b128 v[188:191], v154 offset:50176
	ds_read_b128 v[192:195], v154 offset:51200
	ds_read_b128 v[196:199], v154 offset:52224
	ds_read_b128 v[200:203], v154 offset:53248
	ds_read_b128 v[204:207], v154 offset:54272
	ds_read_b128 v[208:211], v154 offset:55296
	ds_read_b128 v[212:215], v154 offset:56320
	global_load_lds_dwordx4 v136, vcc
	s_mov_b32 m0, s51
	s_nop 0
	global_load_lds_dwordx4 v132, vcc
	s_barrier
	s_waitcnt lgkmcnt(0)
	v_mfma_f32_16x16x32_bf16 v[62:65], v[146:149], v[174:177], v[62:65]
	v_mfma_f32_16x16x32_bf16 v[58:61], v[166:169], v[174:177], v[58:61]
	v_mfma_f32_16x16x32_bf16 v[46:49], v[146:149], v[192:195], v[46:49]
	v_mfma_f32_16x16x32_bf16 v[42:45], v[166:169], v[192:195], v[42:45]
	v_mfma_f32_16x16x32_bf16 v[30:33], v[146:149], v[200:203], v[30:33]
	v_mfma_f32_16x16x32_bf16 v[26:29], v[166:169], v[200:203], v[26:29]
	v_mfma_f32_16x16x32_bf16 v[14:17], v[146:149], v[208:211], v[14:17]
	v_mfma_f32_16x16x32_bf16 v[10:13], v[166:169], v[208:211], v[10:13]
	v_mfma_f32_16x16x32_bf16 v[62:65], v[162:165], v[188:191], v[62:65]
	v_mfma_f32_16x16x32_bf16 v[58:61], v[170:173], v[188:191], v[58:61]
	v_mfma_f32_16x16x32_bf16 v[46:49], v[162:165], v[196:199], v[46:49]
	v_mfma_f32_16x16x32_bf16 v[42:45], v[170:173], v[196:199], v[42:45]
	v_mfma_f32_16x16x32_bf16 v[30:33], v[162:165], v[204:207], v[30:33]
	v_mfma_f32_16x16x32_bf16 v[26:29], v[170:173], v[204:207], v[26:29]
	v_mfma_f32_16x16x32_bf16 v[14:17], v[162:165], v[212:215], v[14:17]
	v_mfma_f32_16x16x32_bf16 v[10:13], v[170:173], v[212:215], v[10:13]
	s_barrier
; __device__ __forceinline__ unsigned cvt_pk_bf16(float lo, float hi) { unsigned r; asm volatile("v_cvt_pk_bf16_f32 %0, %1, %2" : "=v"(r) : "v"(lo), "v"(hi)); return r; }
; #define PG8_STAGE(bufoff, gbase, voff) do { _Pragma("unroll") for (int _i = 0; _i < 2; ++_i) \
;         __builtin_amdgcn_global_load_lds((const unsigned*)((const char*)(gbase) + (voff)[_i]), (LAS unsigned*)(lds + (bufoff) + ldsw + _i * 8192), 16, 0, 0); } while (0)
; #define PG8_MMA(ai, bj, At, Bt) do { __builtin_amdgcn_s_setprio(1); _Pragma("unroll") for (int m = 0; m < 4; ++m) _Pragma("unroll") for (int n = 0; n < 2; ++n) _Pragma("unroll") for (int k = 0; k < 2; ++k) \
;         acc[ai][bj][m][n] = __builtin_amdgcn_mfma_f32_16x16x32_bf16(Bt[n][k], At[m][k], acc[ai][bj][m][n], 0, 0, 0); __builtin_amdgcn_s_setprio(0); } while (0)
; #define PG8_WAIT_V(n) asm volatile("s_waitcnt vmcnt(" #n ")" ::: "memory")
; #define PG8_BAR __builtin_amdgcn_s_barrier()
; template <class Epi>
; __device__ __forceinline__ void gemm_phase(LAS unsigned char* lds, const Gemm g, const StaticOrder& S, const Epi& E) {
;     ...
;             PG8_STAGE(PG8_SB(1, 1), b3 + hstepB, voffB);
;             PG8_WAIT_V(6); PG8_BAR; PG8_MMA(1, 1, At, B1); PG8_BAR;
;     __device__ __forceinline__ void operator()(const f32x4 (&acc)[2][2][4][2], const Unit& u, int wr, int wc, int fr, int fq, const Pre& pp) const {
;         const int row0 = u.pm * BM + wr * 64 + fr, col0 = u.pn * BM + wc * 32 + 8 * fq;
;         const bool gm = (UG != nullptr) && (u.pn < DE / BM);
;         const float (&rs)[8] = pp.rs;
; #pragma unroll
;         for (int ai = 0; ai < 2; ++ai)
; #pragma unroll
;             for (int m = 0; m < 4; ++m) { const int r = row0 + ai * HALF + m * 16; const float inv = rsqrtf(rs[ai * 4 + m] * (1.0f / DM) + EPS);
; #pragma unroll
;                 for (int bj = 0; bj < 2; ++bj) { const f32x4 v0 = acc[ai][bj][m][0] * inv, v1 = acc[ai][bj][m][1] * inv; const int c = col0 + bj * HALF;
;                     u32x4 w; w.x = cvt_pk_bf16(v0[0], v0[1]); w.y = cvt_pk_bf16(v0[2], v0[3]); w.z = cvt_pk_bf16(v1[0], v1[1]); w.w = cvt_pk_bf16(v1[2], v1[3]);
;                     bf16_t* dst = gm ? UG + (size_t)(c >> 4) * GSTR + r * 16 + (c & 15) : O + (size_t)r * DE2 + c;
;                     *(u32x4*)dst = w; } }
	s_add_u32 s4, s4, 0x80080
	s_addc_u32 s5, s5, 0
	s_add_i32 s24, s24, s45
	s_mov_b32 m0, s24
	s_nop 0
	global_load_lds_dwordx4 v134, s[4:5]
	s_add_i32 m0, s24, 0x2000
	s_nop 0
	global_load_lds_dwordx4 v130, s[4:5]
	s_waitcnt vmcnt(6)
	s_barrier
	v_mfma_f32_16x16x32_bf16 v[54:57], v[216:219], v[174:177], v[54:57]
	v_mfma_f32_16x16x32_bf16 v[50:53], v[224:227], v[174:177], v[50:53]
	v_mfma_f32_16x16x32_bf16 v[38:41], v[216:219], v[192:195], v[38:41]
	v_mfma_f32_16x16x32_bf16 v[34:37], v[224:227], v[192:195], v[34:37]
	v_mfma_f32_16x16x32_bf16 v[22:25], v[216:219], v[200:203], v[22:25]
	v_mfma_f32_16x16x32_bf16 v[18:21], v[224:227], v[200:203], v[18:21]
	v_mfma_f32_16x16x32_bf16 v[6:9], v[216:219], v[208:211], v[6:9]
	v_mfma_f32_16x16x32_bf16 v[2:5], v[224:227], v[208:211], v[2:5]
	v_mfma_f32_16x16x32_bf16 v[54:57], v[220:223], v[188:191], v[54:57]
	v_mfma_f32_16x16x32_bf16 v[50:53], v[228:231], v[188:191], v[50:53]
	v_mfma_f32_16x16x32_bf16 v[38:41], v[220:223], v[196:199], v[38:41]
	v_mfma_f32_16x16x32_bf16 v[34:37], v[228:231], v[196:199], v[34:37]
	v_mfma_f32_16x16x32_bf16 v[22:25], v[220:223], v[204:207], v[22:25]
	v_mfma_f32_16x16x32_bf16 v[18:21], v[228:231], v[204:207], v[18:21]
	v_mfma_f32_16x16x32_bf16 v[6:9], v[220:223], v[212:215], v[6:9]
	v_mfma_f32_16x16x32_bf16 v[2:5], v[228:231], v[212:215], v[2:5]
	s_add_i32 s59, s59, 2
	s_add_u32 s57, s57, 0x100
	s_addc_u32 s58, s58, 0
	s_cmp_gt_u32 s59, 29
	s_mov_b64 s[38:39], s[42:43]
	s_barrier
	s_cbranch_scc0 .LBB0_158
	v_readlane_b32 s38, v254, 47
	v_readlane_b32 s39, v254, 48
	s_cmp_gt_i32 s53, 15
	v_lshl_add_u32 v146, s54, 8, v139
	s_cselect_b64 s[4:5], -1, 0
	v_lshl_or_b32 v144, s53, 8, v153
	s_xor_b64 s[38:39], s[38:39], -1
	s_or_b64 s[4:5], s[38:39], s[4:5]
	s_and_b64 vcc, exec, s[4:5]
	s_cbranch_vccz .Lepi_in_gm
	v_fmamk_f32 v0, v145, 0x3a000000, v233
	v_cmp_gt_f32_e32 vcc, s66, v0
	v_mul_f32_e32 v162, 0x4b800000, v0
	v_lshlrev_b32_e32 v147, 14, v146
	v_cndmask_b32_e32 v0, v0, v162, vcc
	v_rsq_f32_e32 v0, v0
	v_lshl_add_u32 v147, v144, 1, v147
	v_mul_f32_e32 v162, 0x45800000, v0
	v_cndmask_b32_e32 v148, v0, v162, vcc
	v_pk_mul_f32 v[126:127], v[148:149], v[126:127] op_sel_hi:[0,1]
	v_pk_mul_f32 v[128:129], v[148:149], v[128:129] op_sel_hi:[0,1]
	v_fmamk_f32 v0, v161, 0x3a000000, v233
	v_pk_mul_f32 v[122:123], v[148:149], v[122:123] op_sel_hi:[0,1]
	v_pk_mul_f32 v[124:125], v[148:149], v[124:125] op_sel_hi:[0,1]
	v_cmp_gt_f32_e32 vcc, s66, v0
	v_cvt_pk_bf16_f32 v125, v124, v125
	v_cvt_pk_bf16_f32 v124, v122, v123
	v_mul_f32_e32 v162, 0x4b800000, v0
	v_cvt_pk_bf16_f32 v122, v126, v127
	v_cvt_pk_bf16_f32 v123, v128, v129
	global_store_dwordx4 v147, v[122:125], s[16:17]
	v_pk_mul_f32 v[118:119], v[148:149], v[118:119] op_sel_hi:[0,1]
	v_cndmask_b32_e32 v0, v0, v162, vcc
	v_pk_mul_f32 v[120:121], v[148:149], v[120:121] op_sel_hi:[0,1]
	v_pk_mul_f32 v[114:115], v[148:149], v[114:115] op_sel_hi:[0,1]
	v_rsq_f32_e32 v0, v0
	v_pk_mul_f32 v[116:117], v[148:149], v[116:117] op_sel_hi:[0,1]
	v_cvt_pk_bf16_f32 v117, v116, v117
	v_cvt_pk_bf16_f32 v116, v114, v115
	v_cvt_pk_bf16_f32 v114, v118, v119
	v_mul_f32_e32 v162, 0x45800000, v0
	v_cvt_pk_bf16_f32 v115, v120, v121
	global_store_dwordx4 v147, v[114:117], s[16:17] offset:256
	v_cndmask_b32_e32 v150, v0, v162, vcc
	v_add_u32_e32 v163, 0x40000, v147
	v_pk_mul_f32 v[110:111], v[150:151], v[110:111] op_sel_hi:[0,1]
	v_fmamk_f32 v0, v160, 0x3a000000, v233
	v_pk_mul_f32 v[112:113], v[150:151], v[112:113] op_sel_hi:[0,1]
	v_pk_mul_f32 v[106:107], v[150:151], v[106:107] op_sel_hi:[0,1]
	v_cmp_gt_f32_e32 vcc, s66, v0
	v_pk_mul_f32 v[108:109], v[150:151], v[108:109] op_sel_hi:[0,1]
	v_cvt_pk_bf16_f32 v109, v108, v109
	v_mul_f32_e32 v162, 0x4b800000, v0
	v_cvt_pk_bf16_f32 v108, v106, v107
	v_cvt_pk_bf16_f32 v106, v110, v111
	v_cvt_pk_bf16_f32 v107, v112, v113
	global_store_dwordx4 v163, v[106:109], s[16:17]
	v_cndmask_b32_e32 v0, v0, v162, vcc
	v_pk_mul_f32 v[102:103], v[150:151], v[102:103] op_sel_hi:[0,1]
	v_pk_mul_f32 v[104:105], v[150:151], v[104:105] op_sel_hi:[0,1]
	v_rsq_f32_e32 v0, v0
	v_pk_mul_f32 v[98:99], v[150:151], v[98:99] op_sel_hi:[0,1]
	v_pk_mul_f32 v[100:101], v[150:151], v[100:101] op_sel_hi:[0,1]
	v_cvt_pk_bf16_f32 v101, v100, v101
	v_cvt_pk_bf16_f32 v100, v98, v99
	v_mul_f32_e32 v162, 0x45800000, v0
	v_cvt_pk_bf16_f32 v98, v102, v103
	v_cvt_pk_bf16_f32 v99, v104, v105
	v_cndmask_b32_e32 v148, v0, v162, vcc
	global_store_dwordx4 v163, v[98:101], s[16:17] offset:256
	v_add_u32_e32 v163, 0x80000, v147
	v_pk_mul_f32 v[94:95], v[148:149], v[94:95] op_sel_hi:[0,1]
	v_fmamk_f32 v0, v159, 0x3a000000, v233
	v_pk_mul_f32 v[96:97], v[148:149], v[96:97] op_sel_hi:[0,1]
	v_pk_mul_f32 v[90:91], v[148:149], v[90:91] op_sel_hi:[0,1]
	v_cmp_gt_f32_e32 vcc, s66, v0
	v_pk_mul_f32 v[92:93], v[148:149], v[92:93] op_sel_hi:[0,1]
	v_cvt_pk_bf16_f32 v93, v92, v93
	v_mul_f32_e32 v162, 0x4b800000, v0
	v_cvt_pk_bf16_f32 v92, v90, v91
	v_cvt_pk_bf16_f32 v90, v94, v95
	v_cvt_pk_bf16_f32 v91, v96, v97
	global_store_dwordx4 v163, v[90:93], s[16:17]
	v_cndmask_b32_e32 v0, v0, v162, vcc
	v_pk_mul_f32 v[86:87], v[148:149], v[86:87] op_sel_hi:[0,1]
	v_pk_mul_f32 v[88:89], v[148:149], v[88:89] op_sel_hi:[0,1]
	v_rsq_f32_e32 v0, v0
	v_pk_mul_f32 v[82:83], v[148:149], v[82:83] op_sel_hi:[0,1]
	v_pk_mul_f32 v[84:85], v[148:149], v[84:85] op_sel_hi:[0,1]
	v_cvt_pk_bf16_f32 v85, v84, v85
	v_cvt_pk_bf16_f32 v84, v82, v83
	v_mul_f32_e32 v162, 0x45800000, v0
	v_cvt_pk_bf16_f32 v82, v86, v87
	v_cvt_pk_bf16_f32 v83, v88, v89
	v_cndmask_b32_e32 v150, v0, v162, vcc
	global_store_dwordx4 v163, v[82:85], s[16:17] offset:256
	v_add_u32_e32 v163, 0xc0000, v147
; __device__ __forceinline__ unsigned cvt_pk_bf16(float lo, float hi) { unsigned r; asm volatile("v_cvt_pk_bf16_f32 %0, %1, %2" : "=v"(r) : "v"(lo), "v"(hi)); return r; }
;     __device__ __forceinline__ void operator()(const f32x4 (&acc)[2][2][4][2], const Unit& u, int wr, int wc, int fr, int fq, const Pre& pp) const {
;     ...
;         for (int ai = 0; ai < 2; ++ai)
; #pragma unroll
;             for (int m = 0; m < 4; ++m) { const int r = row0 + ai * HALF + m * 16; const float inv = rsqrtf(rs[ai * 4 + m] * (1.0f / DM) + EPS);
; #pragma unroll
;                 for (int bj = 0; bj < 2; ++bj) { const f32x4 v0 = acc[ai][bj][m][0] * inv, v1 = acc[ai][bj][m][1] * inv; const int c = col0 + bj * HALF;
;                     u32x4 w; w.x = cvt_pk_bf16(v0[0], v0[1]); w.y = cvt_pk_bf16(v0[2], v0[3]); w.z = cvt_pk_bf16(v1[0], v1[1]); w.w = cvt_pk_bf16(v1[2], v1[3]);
;                     bf16_t* dst = gm ? UG + (size_t)(c >> 4) * GSTR + r * 16 + (c & 15) : O + (size_t)r * DE2 + c;
;                     *(u32x4*)dst = w; } }
	v_pk_mul_f32 v[78:79], v[150:151], v[78:79] op_sel_hi:[0,1]
	v_fmamk_f32 v0, v158, 0x3a000000, v233
	v_pk_mul_f32 v[80:81], v[150:151], v[80:81] op_sel_hi:[0,1]
	v_pk_mul_f32 v[74:75], v[150:151], v[74:75] op_sel_hi:[0,1]
	v_cmp_gt_f32_e32 vcc, s66, v0
	v_pk_mul_f32 v[76:77], v[150:151], v[76:77] op_sel_hi:[0,1]
	v_cvt_pk_bf16_f32 v77, v76, v77
	v_mul_f32_e32 v162, 0x4b800000, v0
	v_cvt_pk_bf16_f32 v76, v74, v75
	v_cvt_pk_bf16_f32 v74, v78, v79
	v_cvt_pk_bf16_f32 v75, v80, v81
	global_store_dwordx4 v163, v[74:77], s[16:17]
	v_cndmask_b32_e32 v0, v0, v162, vcc
	v_pk_mul_f32 v[70:71], v[150:151], v[70:71] op_sel_hi:[0,1]
	v_pk_mul_f32 v[72:73], v[150:151], v[72:73] op_sel_hi:[0,1]
	v_rsq_f32_e32 v0, v0
	v_pk_mul_f32 v[66:67], v[150:151], v[66:67] op_sel_hi:[0,1]
	v_pk_mul_f32 v[68:69], v[150:151], v[68:69] op_sel_hi:[0,1]
	v_cvt_pk_bf16_f32 v69, v68, v69
	v_cvt_pk_bf16_f32 v68, v66, v67
	v_mul_f32_e32 v162, 0x45800000, v0
	v_cvt_pk_bf16_f32 v66, v70, v71
	v_cvt_pk_bf16_f32 v67, v72, v73
	v_cndmask_b32_e32 v148, v0, v162, vcc
	global_store_dwordx4 v163, v[66:69], s[16:17] offset:256
	v_add_u32_e32 v163, 0x200000, v147
	v_pk_mul_f32 v[62:63], v[148:149], v[62:63] op_sel_hi:[0,1]
	v_fmamk_f32 v0, v157, 0x3a000000, v233
	v_pk_mul_f32 v[64:65], v[148:149], v[64:65] op_sel_hi:[0,1]
	v_pk_mul_f32 v[58:59], v[148:149], v[58:59] op_sel_hi:[0,1]
	v_cmp_gt_f32_e32 vcc, s66, v0
	v_pk_mul_f32 v[60:61], v[148:149], v[60:61] op_sel_hi:[0,1]
	v_cvt_pk_bf16_f32 v61, v60, v61
	v_mul_f32_e32 v162, 0x4b800000, v0
	v_cvt_pk_bf16_f32 v60, v58, v59
	v_cvt_pk_bf16_f32 v58, v62, v63
	v_cvt_pk_bf16_f32 v59, v64, v65
	global_store_dwordx4 v163, v[58:61], s[16:17]
	v_cndmask_b32_e32 v0, v0, v162, vcc
	v_pk_mul_f32 v[54:55], v[148:149], v[54:55] op_sel_hi:[0,1]
	v_pk_mul_f32 v[56:57], v[148:149], v[56:57] op_sel_hi:[0,1]
	v_rsq_f32_e32 v0, v0
	v_pk_mul_f32 v[50:51], v[148:149], v[50:51] op_sel_hi:[0,1]
	v_pk_mul_f32 v[52:53], v[148:149], v[52:53] op_sel_hi:[0,1]
	v_cvt_pk_bf16_f32 v53, v52, v53
	v_cvt_pk_bf16_f32 v52, v50, v51
	v_mul_f32_e32 v162, 0x45800000, v0
	v_cvt_pk_bf16_f32 v50, v54, v55
	v_cvt_pk_bf16_f32 v51, v56, v57
	v_cndmask_b32_e32 v150, v0, v162, vcc
	global_store_dwordx4 v163, v[50:53], s[16:17] offset:256
	v_add_u32_e32 v163, 0x240000, v147
	v_pk_mul_f32 v[46:47], v[150:151], v[46:47] op_sel_hi:[0,1]
	v_fmamk_f32 v0, v156, 0x3a000000, v233
	v_pk_mul_f32 v[48:49], v[150:151], v[48:49] op_sel_hi:[0,1]
	v_pk_mul_f32 v[42:43], v[150:151], v[42:43] op_sel_hi:[0,1]
	v_cmp_gt_f32_e32 vcc, s66, v0
	v_pk_mul_f32 v[44:45], v[150:151], v[44:45] op_sel_hi:[0,1]
	v_cvt_pk_bf16_f32 v45, v44, v45
	v_mul_f32_e32 v162, 0x4b800000, v0
	v_cvt_pk_bf16_f32 v44, v42, v43
	v_cvt_pk_bf16_f32 v42, v46, v47
	v_cvt_pk_bf16_f32 v43, v48, v49
	global_store_dwordx4 v163, v[42:45], s[16:17]
	v_cndmask_b32_e32 v0, v0, v162, vcc
	v_pk_mul_f32 v[38:39], v[150:151], v[38:39] op_sel_hi:[0,1]
	v_pk_mul_f32 v[40:41], v[150:151], v[40:41] op_sel_hi:[0,1]
	v_rsq_f32_e32 v0, v0
	v_pk_mul_f32 v[34:35], v[150:151], v[34:35] op_sel_hi:[0,1]
	v_pk_mul_f32 v[36:37], v[150:151], v[36:37] op_sel_hi:[0,1]
	v_cvt_pk_bf16_f32 v37, v36, v37
	v_cvt_pk_bf16_f32 v36, v34, v35
	v_mul_f32_e32 v162, 0x45800000, v0
	v_cvt_pk_bf16_f32 v34, v38, v39
	v_cvt_pk_bf16_f32 v35, v40, v41
	v_cndmask_b32_e32 v148, v0, v162, vcc
	global_store_dwordx4 v163, v[34:37], s[16:17] offset:256
	v_add_u32_e32 v163, 0x280000, v147
	v_pk_mul_f32 v[30:31], v[148:149], v[30:31] op_sel_hi:[0,1]
	v_fmamk_f32 v0, v155, 0x3a000000, v233
	v_pk_mul_f32 v[32:33], v[148:149], v[32:33] op_sel_hi:[0,1]
	v_pk_mul_f32 v[26:27], v[148:149], v[26:27] op_sel_hi:[0,1]
	v_cmp_gt_f32_e32 vcc, s66, v0
	v_pk_mul_f32 v[28:29], v[148:149], v[28:29] op_sel_hi:[0,1]
	v_cvt_pk_bf16_f32 v29, v28, v29
	v_mul_f32_e32 v162, 0x4b800000, v0
	v_cvt_pk_bf16_f32 v28, v26, v27
	v_cvt_pk_bf16_f32 v26, v30, v31
	v_cvt_pk_bf16_f32 v27, v32, v33
	global_store_dwordx4 v163, v[26:29], s[16:17]
	v_cndmask_b32_e32 v0, v0, v162, vcc
	v_pk_mul_f32 v[22:23], v[148:149], v[22:23] op_sel_hi:[0,1]
	v_pk_mul_f32 v[24:25], v[148:149], v[24:25] op_sel_hi:[0,1]
	v_rsq_f32_e32 v0, v0
	v_pk_mul_f32 v[18:19], v[148:149], v[18:19] op_sel_hi:[0,1]
	v_pk_mul_f32 v[20:21], v[148:149], v[20:21] op_sel_hi:[0,1]
	v_cvt_pk_bf16_f32 v21, v20, v21
	v_cvt_pk_bf16_f32 v20, v18, v19
	v_mul_f32_e32 v162, 0x45800000, v0
	v_cvt_pk_bf16_f32 v18, v22, v23
	v_cvt_pk_bf16_f32 v19, v24, v25
	v_cndmask_b32_e32 v150, v0, v162, vcc
	global_store_dwordx4 v163, v[18:21], s[16:17] offset:256
	v_add_u32_e32 v163, 0x2c0000, v147
	v_pk_mul_f32 v[14:15], v[150:151], v[14:15] op_sel_hi:[0,1]
	v_pk_mul_f32 v[16:17], v[150:151], v[16:17] op_sel_hi:[0,1]
	v_pk_mul_f32 v[10:11], v[150:151], v[10:11] op_sel_hi:[0,1]
	v_pk_mul_f32 v[12:13], v[150:151], v[12:13] op_sel_hi:[0,1]
	v_cvt_pk_bf16_f32 v13, v12, v13
	v_cvt_pk_bf16_f32 v12, v10, v11
	v_cvt_pk_bf16_f32 v10, v14, v15
	v_cvt_pk_bf16_f32 v11, v16, v17
	global_store_dwordx4 v163, v[10:13], s[16:17]
	v_pk_mul_f32 v[6:7], v[150:151], v[6:7] op_sel_hi:[0,1]
	v_pk_mul_f32 v[8:9], v[150:151], v[8:9] op_sel_hi:[0,1]
	v_pk_mul_f32 v[2:3], v[150:151], v[2:3] op_sel_hi:[0,1]
	v_pk_mul_f32 v[4:5], v[150:151], v[4:5] op_sel_hi:[0,1]
	v_cvt_pk_bf16_f32 v5, v4, v5
	v_cvt_pk_bf16_f32 v4, v2, v3
	v_cvt_pk_bf16_f32 v2, v6, v7
	v_cvt_pk_bf16_f32 v3, v8, v9
	global_store_dwordx4 v163, v[2:5], s[16:17] offset:256
	s_branch .Lepi_in_done
; __device__ __forceinline__ unsigned cvt_pk_bf16(float lo, float hi) { unsigned r; asm volatile("v_cvt_pk_bf16_f32 %0, %1, %2" : "=v"(r) : "v"(lo), "v"(hi)); return r; }
;     __device__ __forceinline__ void operator()(const f32x4 (&acc)[2][2][4][2], const Unit& u, int wr, int wc, int fr, int fq, const Pre& pp) const {
;         const int row0 = u.pm * BM + wr * 64 + fr, col0 = u.pn * BM + wc * 32 + 8 * fq;
;         const bool gm = (UG != nullptr) && (u.pn < DE / BM);
;         const float (&rs)[8] = pp.rs;
; #pragma unroll
;         for (int ai = 0; ai < 2; ++ai)
; #pragma unroll
;             for (int m = 0; m < 4; ++m) { const int r = row0 + ai * HALF + m * 16; const float inv = rsqrtf(rs[ai * 4 + m] * (1.0f / DM) + EPS);
; #pragma unroll
;                 for (int bj = 0; bj < 2; ++bj) { const f32x4 v0 = acc[ai][bj][m][0] * inv, v1 = acc[ai][bj][m][1] * inv; const int c = col0 + bj * HALF;
;                     u32x4 w; w.x = cvt_pk_bf16(v0[0], v0[1]); w.y = cvt_pk_bf16(v0[2], v0[3]); w.z = cvt_pk_bf16(v1[0], v1[1]); w.w = cvt_pk_bf16(v1[2], v1[3]);
;                     bf16_t* dst = gm ? UG + (size_t)(c >> 4) * GSTR + r * 16 + (c & 15) : O + (size_t)r * DE2 + c;
;                     *(u32x4*)dst = w; } }
.Lepi_in_gm:
	v_fmamk_f32 v0, v145, 0x3a000000, v233
	v_cmp_gt_f32_e32 vcc, s66, v0
	v_mul_f32_e32 v162, 0x4b800000, v0
	v_lshrrev_b32_e32 v147, 4, v144
	v_cndmask_b32_e32 v0, v0, v162, vcc
	v_rsq_f32_e32 v0, v0
	v_mul_u32_u24_e32 v147, 0x41100, v147
	v_mul_f32_e32 v162, 0x45800000, v0
	v_cndmask_b32_e32 v148, v0, v162, vcc
	v_lshl_add_u32 v147, v146, 5, v147
	v_lshl_add_u32 v147, v138, 1, v147
	v_add_u32_e32 v163, 0x208800, v147
	v_add_u32_e32 v144, 0x1000, v147
	v_add_u32_e32 v146, 0x209800, v147
	v_pk_mul_f32 v[126:127], v[148:149], v[126:127] op_sel_hi:[0,1]
	v_pk_mul_f32 v[128:129], v[148:149], v[128:129] op_sel_hi:[0,1]
	v_fmamk_f32 v0, v161, 0x3a000000, v233
	v_pk_mul_f32 v[122:123], v[148:149], v[122:123] op_sel_hi:[0,1]
	v_pk_mul_f32 v[124:125], v[148:149], v[124:125] op_sel_hi:[0,1]
	v_cmp_gt_f32_e32 vcc, s66, v0
	v_cvt_pk_bf16_f32 v125, v124, v125
	v_cvt_pk_bf16_f32 v124, v122, v123
	v_mul_f32_e32 v162, 0x4b800000, v0
	v_cvt_pk_bf16_f32 v122, v126, v127
	v_cvt_pk_bf16_f32 v123, v128, v129
	global_store_dwordx4 v147, v[122:125], s[18:19]
	v_pk_mul_f32 v[118:119], v[148:149], v[118:119] op_sel_hi:[0,1]
	v_cndmask_b32_e32 v0, v0, v162, vcc
	v_pk_mul_f32 v[120:121], v[148:149], v[120:121] op_sel_hi:[0,1]
	v_pk_mul_f32 v[114:115], v[148:149], v[114:115] op_sel_hi:[0,1]
	v_rsq_f32_e32 v0, v0
	v_pk_mul_f32 v[116:117], v[148:149], v[116:117] op_sel_hi:[0,1]
	v_cvt_pk_bf16_f32 v117, v116, v117
	v_cvt_pk_bf16_f32 v116, v114, v115
	v_cvt_pk_bf16_f32 v114, v118, v119
	v_mul_f32_e32 v162, 0x45800000, v0
	v_cvt_pk_bf16_f32 v115, v120, v121
	global_store_dwordx4 v163, v[114:117], s[18:19]
	v_cndmask_b32_e32 v150, v0, v162, vcc
	v_pk_mul_f32 v[110:111], v[150:151], v[110:111] op_sel_hi:[0,1]
	v_pk_mul_f32 v[112:113], v[150:151], v[112:113] op_sel_hi:[0,1]
	v_fmamk_f32 v0, v160, 0x3a000000, v233
	v_pk_mul_f32 v[106:107], v[150:151], v[106:107] op_sel_hi:[0,1]
	v_pk_mul_f32 v[108:109], v[150:151], v[108:109] op_sel_hi:[0,1]
	v_cmp_gt_f32_e32 vcc, s66, v0
	v_cvt_pk_bf16_f32 v109, v108, v109
	v_cvt_pk_bf16_f32 v108, v106, v107
	v_mul_f32_e32 v162, 0x4b800000, v0
	v_cvt_pk_bf16_f32 v106, v110, v111
	v_cvt_pk_bf16_f32 v107, v112, v113
	global_store_dwordx4 v147, v[106:109], s[18:19] offset:512
	v_pk_mul_f32 v[102:103], v[150:151], v[102:103] op_sel_hi:[0,1]
	v_cndmask_b32_e32 v0, v0, v162, vcc
	v_pk_mul_f32 v[104:105], v[150:151], v[104:105] op_sel_hi:[0,1]
	v_pk_mul_f32 v[98:99], v[150:151], v[98:99] op_sel_hi:[0,1]
	v_rsq_f32_e32 v0, v0
	v_pk_mul_f32 v[100:101], v[150:151], v[100:101] op_sel_hi:[0,1]
	v_cvt_pk_bf16_f32 v101, v100, v101
	v_cvt_pk_bf16_f32 v100, v98, v99
	v_cvt_pk_bf16_f32 v98, v102, v103
	v_mul_f32_e32 v162, 0x45800000, v0
	v_cvt_pk_bf16_f32 v99, v104, v105
	global_store_dwordx4 v163, v[98:101], s[18:19] offset:512
	v_cndmask_b32_e32 v148, v0, v162, vcc
	v_pk_mul_f32 v[94:95], v[148:149], v[94:95] op_sel_hi:[0,1]
	v_pk_mul_f32 v[96:97], v[148:149], v[96:97] op_sel_hi:[0,1]
	v_fmamk_f32 v0, v159, 0x3a000000, v233
	v_pk_mul_f32 v[90:91], v[148:149], v[90:91] op_sel_hi:[0,1]
	v_pk_mul_f32 v[92:93], v[148:149], v[92:93] op_sel_hi:[0,1]
	v_cmp_gt_f32_e32 vcc, s66, v0
	v_cvt_pk_bf16_f32 v93, v92, v93
	v_cvt_pk_bf16_f32 v92, v90, v91
	v_mul_f32_e32 v162, 0x4b800000, v0
	v_cvt_pk_bf16_f32 v90, v94, v95
	v_cvt_pk_bf16_f32 v91, v96, v97
	global_store_dwordx4 v147, v[90:93], s[18:19] offset:1024
	v_pk_mul_f32 v[86:87], v[148:149], v[86:87] op_sel_hi:[0,1]
	v_cndmask_b32_e32 v0, v0, v162, vcc
	v_pk_mul_f32 v[88:89], v[148:149], v[88:89] op_sel_hi:[0,1]
	v_pk_mul_f32 v[82:83], v[148:149], v[82:83] op_sel_hi:[0,1]
	v_rsq_f32_e32 v0, v0
	v_pk_mul_f32 v[84:85], v[148:149], v[84:85] op_sel_hi:[0,1]
	v_cvt_pk_bf16_f32 v85, v84, v85
	v_cvt_pk_bf16_f32 v84, v82, v83
	v_cvt_pk_bf16_f32 v82, v86, v87
	v_mul_f32_e32 v162, 0x45800000, v0
	v_cvt_pk_bf16_f32 v83, v88, v89
	global_store_dwordx4 v163, v[82:85], s[18:19] offset:1024
	v_cndmask_b32_e32 v150, v0, v162, vcc
	v_pk_mul_f32 v[78:79], v[150:151], v[78:79] op_sel_hi:[0,1]
	v_pk_mul_f32 v[80:81], v[150:151], v[80:81] op_sel_hi:[0,1]
	v_fmamk_f32 v0, v158, 0x3a000000, v233
	v_pk_mul_f32 v[74:75], v[150:151], v[74:75] op_sel_hi:[0,1]
	v_pk_mul_f32 v[76:77], v[150:151], v[76:77] op_sel_hi:[0,1]
	v_cmp_gt_f32_e32 vcc, s66, v0
	v_cvt_pk_bf16_f32 v77, v76, v77
	v_cvt_pk_bf16_f32 v76, v74, v75
	v_mul_f32_e32 v162, 0x4b800000, v0
	v_cvt_pk_bf16_f32 v74, v78, v79
	v_cvt_pk_bf16_f32 v75, v80, v81
	global_store_dwordx4 v147, v[74:77], s[18:19] offset:1536
	v_pk_mul_f32 v[70:71], v[150:151], v[70:71] op_sel_hi:[0,1]
	v_cndmask_b32_e32 v0, v0, v162, vcc
; __device__ __forceinline__ unsigned cvt_pk_bf16(float lo, float hi) { unsigned r; asm volatile("v_cvt_pk_bf16_f32 %0, %1, %2" : "=v"(r) : "v"(lo), "v"(hi)); return r; }
;     __device__ __forceinline__ void operator()(const f32x4 (&acc)[2][2][4][2], const Unit& u, int wr, int wc, int fr, int fq, const Pre& pp) const {
;     ...
;         for (int ai = 0; ai < 2; ++ai)
; #pragma unroll
;             for (int m = 0; m < 4; ++m) { const int r = row0 + ai * HALF + m * 16; const float inv = rsqrtf(rs[ai * 4 + m] * (1.0f / DM) + EPS);
; #pragma unroll
;                 for (int bj = 0; bj < 2; ++bj) { const f32x4 v0 = acc[ai][bj][m][0] * inv, v1 = acc[ai][bj][m][1] * inv; const int c = col0 + bj * HALF;
;                     u32x4 w; w.x = cvt_pk_bf16(v0[0], v0[1]); w.y = cvt_pk_bf16(v0[2], v0[3]); w.z = cvt_pk_bf16(v1[0], v1[1]); w.w = cvt_pk_bf16(v1[2], v1[3]);
;                     bf16_t* dst = gm ? UG + (size_t)(c >> 4) * GSTR + r * 16 + (c & 15) : O + (size_t)r * DE2 + c;
;                     *(u32x4*)dst = w; } }
	v_pk_mul_f32 v[72:73], v[150:151], v[72:73] op_sel_hi:[0,1]
	v_pk_mul_f32 v[66:67], v[150:151], v[66:67] op_sel_hi:[0,1]
	v_rsq_f32_e32 v0, v0
	v_pk_mul_f32 v[68:69], v[150:151], v[68:69] op_sel_hi:[0,1]
	v_cvt_pk_bf16_f32 v69, v68, v69
	v_cvt_pk_bf16_f32 v68, v66, v67
	v_cvt_pk_bf16_f32 v66, v70, v71
	v_mul_f32_e32 v162, 0x45800000, v0
	v_cvt_pk_bf16_f32 v67, v72, v73
	global_store_dwordx4 v163, v[66:69], s[18:19] offset:1536
	v_cndmask_b32_e32 v148, v0, v162, vcc
	v_pk_mul_f32 v[62:63], v[148:149], v[62:63] op_sel_hi:[0,1]
	v_pk_mul_f32 v[64:65], v[148:149], v[64:65] op_sel_hi:[0,1]
	v_fmamk_f32 v0, v157, 0x3a000000, v233
	v_pk_mul_f32 v[58:59], v[148:149], v[58:59] op_sel_hi:[0,1]
	v_pk_mul_f32 v[60:61], v[148:149], v[60:61] op_sel_hi:[0,1]
	v_cmp_gt_f32_e32 vcc, s66, v0
	v_cvt_pk_bf16_f32 v61, v60, v61
	v_cvt_pk_bf16_f32 v60, v58, v59
	v_mul_f32_e32 v162, 0x4b800000, v0
	v_cvt_pk_bf16_f32 v58, v62, v63
	v_cvt_pk_bf16_f32 v59, v64, v65
	global_store_dwordx4 v144, v[58:61], s[18:19]
	v_pk_mul_f32 v[54:55], v[148:149], v[54:55] op_sel_hi:[0,1]
	v_cndmask_b32_e32 v0, v0, v162, vcc
	v_pk_mul_f32 v[56:57], v[148:149], v[56:57] op_sel_hi:[0,1]
	v_pk_mul_f32 v[50:51], v[148:149], v[50:51] op_sel_hi:[0,1]
	v_rsq_f32_e32 v0, v0
	v_pk_mul_f32 v[52:53], v[148:149], v[52:53] op_sel_hi:[0,1]
	v_cvt_pk_bf16_f32 v53, v52, v53
	v_cvt_pk_bf16_f32 v52, v50, v51
	v_cvt_pk_bf16_f32 v50, v54, v55
	v_mul_f32_e32 v162, 0x45800000, v0
	v_cvt_pk_bf16_f32 v51, v56, v57
	global_store_dwordx4 v146, v[50:53], s[18:19]
	v_cndmask_b32_e32 v150, v0, v162, vcc
	v_pk_mul_f32 v[46:47], v[150:151], v[46:47] op_sel_hi:[0,1]
	v_pk_mul_f32 v[48:49], v[150:151], v[48:49] op_sel_hi:[0,1]
	v_fmamk_f32 v0, v156, 0x3a000000, v233
	v_pk_mul_f32 v[42:43], v[150:151], v[42:43] op_sel_hi:[0,1]
	v_pk_mul_f32 v[44:45], v[150:151], v[44:45] op_sel_hi:[0,1]
	v_cmp_gt_f32_e32 vcc, s66, v0
	v_cvt_pk_bf16_f32 v45, v44, v45
	v_cvt_pk_bf16_f32 v44, v42, v43
	v_mul_f32_e32 v162, 0x4b800000, v0
	v_cvt_pk_bf16_f32 v42, v46, v47
	v_cvt_pk_bf16_f32 v43, v48, v49
	global_store_dwordx4 v144, v[42:45], s[18:19] offset:512
	v_pk_mul_f32 v[38:39], v[150:151], v[38:39] op_sel_hi:[0,1]
	v_cndmask_b32_e32 v0, v0, v162, vcc
	v_pk_mul_f32 v[40:41], v[150:151], v[40:41] op_sel_hi:[0,1]
	v_pk_mul_f32 v[34:35], v[150:151], v[34:35] op_sel_hi:[0,1]
	v_rsq_f32_e32 v0, v0
	v_pk_mul_f32 v[36:37], v[150:151], v[36:37] op_sel_hi:[0,1]
	v_cvt_pk_bf16_f32 v37, v36, v37
	v_cvt_pk_bf16_f32 v36, v34, v35
	v_cvt_pk_bf16_f32 v34, v38, v39
	v_mul_f32_e32 v162, 0x45800000, v0
	v_cvt_pk_bf16_f32 v35, v40, v41
	global_store_dwordx4 v146, v[34:37], s[18:19] offset:512
	v_cndmask_b32_e32 v148, v0, v162, vcc
	v_pk_mul_f32 v[30:31], v[148:149], v[30:31] op_sel_hi:[0,1]
	v_pk_mul_f32 v[32:33], v[148:149], v[32:33] op_sel_hi:[0,1]
	v_fmamk_f32 v0, v155, 0x3a000000, v233
	v_pk_mul_f32 v[26:27], v[148:149], v[26:27] op_sel_hi:[0,1]
	v_pk_mul_f32 v[28:29], v[148:149], v[28:29] op_sel_hi:[0,1]
	v_cmp_gt_f32_e32 vcc, s66, v0
	v_cvt_pk_bf16_f32 v29, v28, v29
	v_cvt_pk_bf16_f32 v28, v26, v27
	v_mul_f32_e32 v162, 0x4b800000, v0
	v_cvt_pk_bf16_f32 v26, v30, v31
	v_cvt_pk_bf16_f32 v27, v32, v33
	global_store_dwordx4 v144, v[26:29], s[18:19] offset:1024
	v_pk_mul_f32 v[22:23], v[148:149], v[22:23] op_sel_hi:[0,1]
	v_cndmask_b32_e32 v0, v0, v162, vcc
	v_pk_mul_f32 v[24:25], v[148:149], v[24:25] op_sel_hi:[0,1]
	v_pk_mul_f32 v[18:19], v[148:149], v[18:19] op_sel_hi:[0,1]
	v_rsq_f32_e32 v0, v0
	v_pk_mul_f32 v[20:21], v[148:149], v[20:21] op_sel_hi:[0,1]
	v_cvt_pk_bf16_f32 v21, v20, v21
	v_cvt_pk_bf16_f32 v20, v18, v19
	v_cvt_pk_bf16_f32 v18, v22, v23
	v_mul_f32_e32 v162, 0x45800000, v0
	v_cvt_pk_bf16_f32 v19, v24, v25
	global_store_dwordx4 v146, v[18:21], s[18:19] offset:1024
	v_cndmask_b32_e32 v150, v0, v162, vcc
	v_pk_mul_f32 v[14:15], v[150:151], v[14:15] op_sel_hi:[0,1]
	v_pk_mul_f32 v[16:17], v[150:151], v[16:17] op_sel_hi:[0,1]
	v_pk_mul_f32 v[10:11], v[150:151], v[10:11] op_sel_hi:[0,1]
	v_pk_mul_f32 v[12:13], v[150:151], v[12:13] op_sel_hi:[0,1]
	v_cvt_pk_bf16_f32 v13, v12, v13
	v_cvt_pk_bf16_f32 v12, v10, v11
	v_cvt_pk_bf16_f32 v10, v14, v15
	v_cvt_pk_bf16_f32 v11, v16, v17
	global_store_dwordx4 v144, v[10:13], s[18:19] offset:1536
	v_pk_mul_f32 v[6:7], v[150:151], v[6:7] op_sel_hi:[0,1]
	v_pk_mul_f32 v[8:9], v[150:151], v[8:9] op_sel_hi:[0,1]
	v_pk_mul_f32 v[2:3], v[150:151], v[2:3] op_sel_hi:[0,1]
	v_pk_mul_f32 v[4:5], v[150:151], v[4:5] op_sel_hi:[0,1]
	v_cvt_pk_bf16_f32 v5, v4, v5
	v_cvt_pk_bf16_f32 v4, v2, v3
	v_cvt_pk_bf16_f32 v2, v6, v7
	v_cvt_pk_bf16_f32 v3, v8, v9
	global_store_dwordx4 v146, v[2:5], s[18:19] offset:1536
